# S5 input-row loads issued for lanes 0-31 only (lanes 32-63 only meet zero A entries; zeroed once per segment)
# baseline (speedup 1.0000x reference)
; DI void s5_job(const PX& p, int l, int job, unsigned char* smem) {
;     ...
;   for (int seg = 0; seg < 2; seg++) {
;     const int Lseg = seg ? 2048 : 256;
;     const int tokbase = seg ? b * 2048 : NLAT + b * 256;
;     const int nblk = Lseg >> 3;
;     uint4 ucur[8], unext[8];
;     if (active) {
; #pragma unroll
;       for (int s = 0; s < 8; s++) {
;         const int t = dir ? Lseg - 1 - s : s;
;         ucur[s] = *(const uint4*)(Zu + (size_t)(tokbase + t) * 768);
;       }
;     }
; #pragma unroll 1
;     for (int blk = 0; blk < nblk; blk++, gblk++) {
;       float* exb = ex + (gblk & 1) * (32 * 64) + lane;
;       f32x4 yp[8];
;       if (active) {
;         if (blk + 1 < nblk) {
; #pragma unroll
;           for (int s = 0; s < 8; s++) {
;             const int st = (blk + 1) * 8 + s;
;             const int t = dir ? Lseg - 1 - st : st;
;             unext[s] = *(const uint4*)(Zu + (size_t)(tokbase + t) * 768);
;           }
;         }
.LBB0_500:
	s_and_b64 s[2:3], s[14:15], exec
	s_movk_i32 s1, 0x800
	s_cselect_b32 s1, 0x100, s1
	v_cndmask_b32_e64 v2, v160, v161, s[14:15]
	s_and_saveexec_b64 s[12:13], s[4:5]
	s_cbranch_execz .LBB0_502
	s_add_i32 s2, s1, -1
	v_mov_b32_e32 v0, s2
	v_cndmask_b32_e64 v0, v0, 0, s[6:7]
	v_add_u32_e32 v0, v0, v2
	v_mul_i32_i24_e32 v0, 0x300, v0
	s_add_i32 s2, s1, -2
	s_waitcnt vmcnt(6)
	v_lshl_add_u64 v[36:37], v[0:1], 1, v[156:157]
	v_mov_b32_e32 v0, s2
	v_cndmask_b32_e64 v0, v0, 1, s[6:7]
	v_add_u32_e32 v0, v0, v2
	v_mul_i32_i24_e32 v0, 0x300, v0
	s_add_i32 s2, s1, -3
	v_lshl_add_u64 v[38:39], v[0:1], 1, v[156:157]
	v_mov_b32_e32 v0, s2
	v_cndmask_b32_e64 v0, v0, 2, s[6:7]
	v_add_u32_e32 v0, v0, v2
	v_mul_i32_i24_e32 v0, 0x300, v0
	s_add_i32 s2, s1, -4
	s_waitcnt vmcnt(4)
	v_lshl_add_u64 v[52:53], v[0:1], 1, v[156:157]
	v_mov_b32_e32 v0, s2
	v_cndmask_b32_e64 v0, v0, 3, s[6:7]
	v_add_u32_e32 v0, v0, v2
	v_mul_i32_i24_e32 v0, 0x300, v0
	s_add_i32 s2, s1, -5
	v_lshl_add_u64 v[54:55], v[0:1], 1, v[156:157]
	v_mov_b32_e32 v0, s2
	v_cndmask_b32_e64 v0, v0, 4, s[6:7]
	v_add_u32_e32 v0, v0, v2
	v_mul_i32_i24_e32 v0, 0x300, v0
	s_add_i32 s2, s1, -6
	s_waitcnt vmcnt(2)
	v_lshl_add_u64 v[68:69], v[0:1], 1, v[156:157]
	v_mov_b32_e32 v0, s2
	v_cndmask_b32_e64 v0, v0, 5, s[6:7]
	v_add_u32_e32 v0, v0, v2
	v_mul_i32_i24_e32 v0, 0x300, v0
	s_add_i32 s2, s1, -7
	v_lshl_add_u64 v[70:71], v[0:1], 1, v[156:157]
	v_mov_b32_e32 v0, s2
	v_cndmask_b32_e64 v0, v0, 6, s[6:7]
	v_add_u32_e32 v0, v0, v2
	v_mul_i32_i24_e32 v0, 0x300, v0
	s_add_i32 s2, s1, -8
	s_waitcnt vmcnt(0)
	v_lshl_add_u64 v[84:85], v[0:1], 1, v[156:157]
	v_mov_b32_e32 v0, s2
	v_cndmask_b32_e64 v0, v0, 7, s[6:7]
	v_add_u32_e32 v0, v0, v2
	v_mul_i32_i24_e32 v0, 0x300, v0
	v_lshl_add_u64 v[86:87], v[0:1], 1, v[156:157]
	s_mov_b32 exec_hi, 0
	global_load_dwordx4 v[40:43], v[36:37], off
	s_nop 0
	global_load_dwordx4 v[36:39], v[38:39], off
	s_nop 0
	global_load_dwordx4 v[56:59], v[52:53], off
	s_nop 0
	global_load_dwordx4 v[52:55], v[54:55], off
	s_nop 0
	global_load_dwordx4 v[72:75], v[68:69], off
	s_nop 0
	global_load_dwordx4 v[68:71], v[70:71], off
	s_nop 0
	global_load_dwordx4 v[88:91], v[84:85], off
	s_nop 0
	global_load_dwordx4 v[84:87], v[86:87], off
	s_mov_b32 exec_hi, -1
	s_mov_b32 exec_lo, 0
	v_mov_b32_e32 v36, 0
	v_mov_b32_e32 v37, 0
	v_mov_b32_e32 v38, 0
	v_mov_b32_e32 v39, 0
	v_mov_b32_e32 v40, 0
	v_mov_b32_e32 v41, 0
	v_mov_b32_e32 v42, 0
	v_mov_b32_e32 v43, 0
	v_mov_b32_e32 v52, 0
	v_mov_b32_e32 v53, 0
	v_mov_b32_e32 v54, 0
	v_mov_b32_e32 v55, 0
	v_mov_b32_e32 v56, 0
	v_mov_b32_e32 v57, 0
	v_mov_b32_e32 v58, 0
	v_mov_b32_e32 v59, 0
	v_mov_b32_e32 v68, 0
	v_mov_b32_e32 v69, 0
	v_mov_b32_e32 v70, 0
	v_mov_b32_e32 v71, 0
	v_mov_b32_e32 v72, 0
	v_mov_b32_e32 v73, 0
	v_mov_b32_e32 v74, 0
	v_mov_b32_e32 v75, 0
	v_mov_b32_e32 v84, 0
	v_mov_b32_e32 v85, 0
	v_mov_b32_e32 v86, 0
	v_mov_b32_e32 v87, 0
	v_mov_b32_e32 v88, 0
	v_mov_b32_e32 v89, 0
	v_mov_b32_e32 v90, 0
	v_mov_b32_e32 v91, 0
	s_mov_b32 exec_lo, -1
	s_add_i32 s16, s1, -9
	v_mov_b32_e32 v208, s16
	v_cndmask_b32_e64 v208, v208, 8, s[6:7]
	v_add_u32_e32 v208, v208, v2
	v_mad_i64_i32 v[190:191], s[16:17], v208, s81, v[156:157]
	v_mov_b32_e32 v208, 0x600
	v_mov_b32_e32 v209, 0xfffffa00
	v_cndmask_b32_e64 v208, v209, v208, s[6:7]
	v_cndmask_b32_e64 v209, -1, 0, s[6:7]
	v_lshlrev_b64 v[206:207], 3, v[208:209]
	v_lshl_add_u64 v[192:193], v[190:191], 0, v[208:209]
	v_lshl_add_u64 v[194:195], v[192:193], 0, v[208:209]
	v_lshl_add_u64 v[196:197], v[194:195], 0, v[208:209]
	v_lshl_add_u64 v[198:199], v[196:197], 0, v[208:209]
	v_lshl_add_u64 v[200:201], v[198:199], 0, v[208:209]
	v_lshl_add_u64 v[202:203], v[200:201], 0, v[208:209]
	v_lshl_add_u64 v[204:205], v[202:203], 0, v[208:209]
	s_waitcnt vmcnt(0)

; DI unsigned pack2(float a, float b) { f32x2_t v = {a, b}; bf16x2_t r = __builtin_convertvector(v, bf16x2_t); return __builtin_bit_cast(unsigned, r); }
; DI f32x4 mfma16(bf16x8 a, bf16x8 b, f32x4 c) { return __builtin_amdgcn_mfma_f32_16x16x32_bf16(a, b, c, 0, 0, 0); }
; DI void s5_job(const PX& p, int l, int job, unsigned char* smem) {
;     ...
;       if (active) {
;         if (blk + 1 < nblk) {
; #pragma unroll
;           for (int s = 0; s < 8; s++) {
;             const int st = (blk + 1) * 8 + s;
;             const int t = dir ? Lseg - 1 - st : st;
;             unext[s] = *(const uint4*)(Zu + (size_t)(tokbase + t) * 768);
;           }
;         }
; #pragma unroll
;         for (int s = 0; s < 8; s++) {
;           const bf16x8 ub = u4_to_bf8(ucur[s]);
; #pragma unroll
;           for (int tt = 0; tt < 2; tt++) {
;             f32x4 cr, ci;
; #pragma unroll
;             for (int r = 0; r < 4; r++) {
;               cr[r] = lre[tt][r] * sre[tt][r] - lim[tt][r] * sim[tt][r];
;               ci[r] = lre[tt][r] * sim[tt][r] + lim[tt][r] * sre[tt][r];
;             }
;             sre[tt] = mfma16(Are[tt], ub, cr);
;             sim[tt] = mfma16(Aim[tt], ub, ci);
;           }
;           uint4 pr, pi;
;           pr.x = pack2(sre[0][0], sre[0][1]); pr.y = pack2(sre[0][2], sre[0][3]);
;           pr.z = pack2(sre[1][0], sre[1][1]); pr.w = pack2(sre[1][2], sre[1][3]);
;           pi.x = pack2(sim[0][0], sim[0][1]); pi.y = pack2(sim[0][2], sim[0][3]);
;           pi.z = pack2(sim[1][0], sim[1][1]); pi.w = pack2(sim[1][2], sim[1][3]);
;           f32x4 y = f32x4{0.f, 0.f, 0.f, 0.f};
;           y = mfma16(Cf[0], u4_to_bf8(pr), y);
;           y = mfma16(Cf[1], u4_to_bf8(pi), y);
;           yp[s] = y;
;         }
.LBB0_507:
	v_pk_mul_f32 v[92:93], v[146:147], v[122:123]
	v_pk_mul_f32 v[96:97], v[142:143], v[120:121]
	v_pk_fma_f32 v[94:95], v[144:145], v[118:119], v[92:93] neg_lo:[0,0,1] neg_hi:[0,0,1]
	v_pk_fma_f32 v[92:93], v[140:141], v[116:117], v[96:97] neg_lo:[0,0,1] neg_hi:[0,0,1]
	v_pk_mul_f32 v[100:101], v[144:145], v[122:123]
	v_pk_mul_f32 v[104:105], v[150:151], v[112:113]
	s_waitcnt vmcnt(11)
	v_mfma_f32_16x16x32_bf16 v[96:99], v[12:15], v[40:43], v[92:95]
	s_nop 2
	v_mul_f32_e64 v92, v140, v120
	v_mul_f32_e64 v93, v141, v121
	v_pk_fma_f32 v[94:95], v[146:147], v[118:119], v[100:101]
	v_pk_fma_f32 v[92:93], v[142:143], v[116:117], v[92:93]
	s_nop 1
	v_mfma_f32_16x16x32_bf16 v[100:103], v[16:19], v[40:43], v[92:95]
	s_nop 2
	v_mul_f32_e64 v92, v154, v114
	v_mul_f32_e64 v93, v155, v115
	v_pk_mul_f32 v[114:115], v[152:153], v[114:115]
	v_pk_fma_f32 v[94:95], v[152:153], v[110:111], v[92:93] neg_lo:[0,0,1] neg_hi:[0,0,1]
	v_pk_fma_f32 v[92:93], v[148:149], v[108:109], v[104:105] neg_lo:[0,0,1] neg_hi:[0,0,1]
	v_pk_mul_f32 v[116:117], v[142:143], v[100:101]
	s_nop 0
	v_mfma_f32_16x16x32_bf16 v[104:107], v[4:7], v[40:43], v[92:95]
	s_nop 2
	v_mul_f32_e64 v92, v148, v112
	v_mul_f32_e64 v93, v149, v113
	v_pk_fma_f32 v[94:95], v[154:155], v[110:111], v[114:115]
	v_pk_fma_f32 v[92:93], v[150:151], v[108:109], v[92:93]
	v_cvt_pk_bf16_f32 v112, v100, v101
	v_cvt_pk_bf16_f32 v113, v102, v103
	v_mfma_f32_16x16x32_bf16 v[108:111], v[8:11], v[40:43], v[92:95]
	s_mov_b32 exec_hi, 0
	global_load_dwordx4 v[40:43], v[190:191], off
	s_mov_b32 exec_hi, -1
	v_lshl_add_u64 v[190:191], v[190:191], 0, v[206:207]
	s_cmp_lg_u32 s23, 0
	s_cbranch_scc1 .Ls5st_d0
	global_store_dwordx2 v[216:217], v[168:169], off
	s_branch .Ls5st_e0

; DI unsigned pack2(float a, float b) { f32x2_t v = {a, b}; bf16x2_t r = __builtin_convertvector(v, bf16x2_t); return __builtin_bit_cast(unsigned, r); }
; DI f32x4 mfma16(bf16x8 a, bf16x8 b, f32x4 c) { return __builtin_amdgcn_mfma_f32_16x16x32_bf16(a, b, c, 0, 0, 0); }
; DI void s5_job(const PX& p, int l, int job, unsigned char* smem) {
;     ...
;       if (active) {
;         if (blk + 1 < nblk) {
; #pragma unroll
;           for (int s = 0; s < 8; s++) {
;             const int st = (blk + 1) * 8 + s;
;             const int t = dir ? Lseg - 1 - st : st;
;             unext[s] = *(const uint4*)(Zu + (size_t)(tokbase + t) * 768);
;           }
;         }
; #pragma unroll
;         for (int s = 0; s < 8; s++) {
;           const bf16x8 ub = u4_to_bf8(ucur[s]);
; #pragma unroll
;           for (int tt = 0; tt < 2; tt++) {
;             f32x4 cr, ci;
; #pragma unroll
;             for (int r = 0; r < 4; r++) {
;               cr[r] = lre[tt][r] * sre[tt][r] - lim[tt][r] * sim[tt][r];
;               ci[r] = lre[tt][r] * sim[tt][r] + lim[tt][r] * sre[tt][r];
;             }
;             sre[tt] = mfma16(Are[tt], ub, cr);
;             sim[tt] = mfma16(Aim[tt], ub, ci);
;           }
;           uint4 pr, pi;
;           pr.x = pack2(sre[0][0], sre[0][1]); pr.y = pack2(sre[0][2], sre[0][3]);
;           pr.z = pack2(sre[1][0], sre[1][1]); pr.w = pack2(sre[1][2], sre[1][3]);
;           pi.x = pack2(sim[0][0], sim[0][1]); pi.y = pack2(sim[0][2], sim[0][3]);
;           pi.z = pack2(sim[1][0], sim[1][1]); pi.w = pack2(sim[1][2], sim[1][3]);
;           f32x4 y = f32x4{0.f, 0.f, 0.f, 0.f};
;           y = mfma16(Cf[0], u4_to_bf8(pr), y);
;           y = mfma16(Cf[1], u4_to_bf8(pi), y);
;           yp[s] = y;
;         }
.Ls5st_e0:
	v_mul_f32_e64 v100, v140, v100
	v_mul_f32_e64 v101, v141, v101
	s_nop 0
	v_cvt_pk_bf16_f32 v92, v96, v97
	v_cvt_pk_bf16_f32 v93, v98, v99
	v_cvt_pk_bf16_f32 v94, v104, v105
	v_cvt_pk_bf16_f32 v95, v106, v107
	s_nop 0
	v_cvt_pk_bf16_f32 v114, v108, v109
	v_cvt_pk_bf16_f32 v115, v110, v111
	v_mfma_f32_16x16x32_bf16 v[92:95], v[20:23], v[92:95], 0
	s_nop 0
	v_mfma_f32_16x16x32_bf16 v[92:95], v[24:27], v[112:115], v[92:95]
	v_mul_f32_e64 v112, v146, v102
	v_mul_f32_e64 v113, v147, v103
	v_pk_mul_f32 v[102:103], v[144:145], v[102:103]
	v_pk_fma_f32 v[114:115], v[144:145], v[98:99], v[112:113] neg_lo:[0,0,1] neg_hi:[0,0,1]
	v_pk_fma_f32 v[112:113], v[140:141], v[96:97], v[116:117] neg_lo:[0,0,1] neg_hi:[0,0,1]
	v_pk_fma_f32 v[98:99], v[146:147], v[98:99], v[102:103]
	v_pk_fma_f32 v[96:97], v[142:143], v[96:97], v[100:101]
	v_pk_mul_f32 v[116:117], v[150:151], v[108:109]
	s_waitcnt vmcnt(11)
	v_mfma_f32_16x16x32_bf16 v[112:115], v[12:15], v[36:39], v[112:115]
	v_mfma_f32_16x16x32_bf16 v[100:103], v[16:19], v[36:39], v[96:99]
	s_nop 2
	v_mul_f32_e64 v96, v154, v110
	v_mul_f32_e64 v97, v155, v111
	v_pk_mul_f32 v[110:111], v[152:153], v[110:111]
	v_pk_fma_f32 v[98:99], v[152:153], v[106:107], v[96:97] neg_lo:[0,0,1] neg_hi:[0,0,1]
	v_pk_fma_f32 v[96:97], v[148:149], v[104:105], v[116:117] neg_lo:[0,0,1] neg_hi:[0,0,1]
	v_pk_mul_f32 v[120:121], v[142:143], v[100:101]
	s_nop 0
	v_mfma_f32_16x16x32_bf16 v[116:119], v[4:7], v[36:39], v[96:99]
	s_nop 2
	v_mul_f32_e64 v96, v148, v108
	v_mul_f32_e64 v97, v149, v109
	v_pk_fma_f32 v[98:99], v[154:155], v[106:107], v[110:111]
	v_pk_fma_f32 v[96:97], v[150:151], v[104:105], v[96:97]
	v_cvt_pk_bf16_f32 v108, v100, v101
	v_cvt_pk_bf16_f32 v109, v102, v103
	v_mfma_f32_16x16x32_bf16 v[104:107], v[8:11], v[36:39], v[96:99]
	s_mov_b32 exec_hi, 0
	global_load_dwordx4 v[36:39], v[192:193], off
	s_mov_b32 exec_hi, -1
	v_lshl_add_u64 v[192:193], v[192:193], 0, v[206:207]
	s_cmp_lg_u32 s23, 0
	s_cbranch_scc1 .Ls5st_d1
	global_store_dwordx2 v[218:219], v[172:173], off
	s_branch .Ls5st_e1

; DI unsigned pack2(float a, float b) { f32x2_t v = {a, b}; bf16x2_t r = __builtin_convertvector(v, bf16x2_t); return __builtin_bit_cast(unsigned, r); }
; DI f32x4 mfma16(bf16x8 a, bf16x8 b, f32x4 c) { return __builtin_amdgcn_mfma_f32_16x16x32_bf16(a, b, c, 0, 0, 0); }
; DI void s5_job(const PX& p, int l, int job, unsigned char* smem) {
;     ...
;       if (active) {
;         if (blk + 1 < nblk) {
; #pragma unroll
;           for (int s = 0; s < 8; s++) {
;             const int st = (blk + 1) * 8 + s;
;             const int t = dir ? Lseg - 1 - st : st;
;             unext[s] = *(const uint4*)(Zu + (size_t)(tokbase + t) * 768);
;           }
;         }
; #pragma unroll
;         for (int s = 0; s < 8; s++) {
;           const bf16x8 ub = u4_to_bf8(ucur[s]);
; #pragma unroll
;           for (int tt = 0; tt < 2; tt++) {
;             f32x4 cr, ci;
; #pragma unroll
;             for (int r = 0; r < 4; r++) {
;               cr[r] = lre[tt][r] * sre[tt][r] - lim[tt][r] * sim[tt][r];
;               ci[r] = lre[tt][r] * sim[tt][r] + lim[tt][r] * sre[tt][r];
;             }
;             sre[tt] = mfma16(Are[tt], ub, cr);
;             sim[tt] = mfma16(Aim[tt], ub, ci);
;           }
;           uint4 pr, pi;
;           pr.x = pack2(sre[0][0], sre[0][1]); pr.y = pack2(sre[0][2], sre[0][3]);
;           pr.z = pack2(sre[1][0], sre[1][1]); pr.w = pack2(sre[1][2], sre[1][3]);
;           pi.x = pack2(sim[0][0], sim[0][1]); pi.y = pack2(sim[0][2], sim[0][3]);
;           pi.z = pack2(sim[1][0], sim[1][1]); pi.w = pack2(sim[1][2], sim[1][3]);
;           f32x4 y = f32x4{0.f, 0.f, 0.f, 0.f};
;           y = mfma16(Cf[0], u4_to_bf8(pr), y);
;           y = mfma16(Cf[1], u4_to_bf8(pi), y);
;           yp[s] = y;
;         }
.Ls5st_e1:
	v_mul_f32_e64 v100, v140, v100
	v_mul_f32_e64 v101, v141, v101
	v_pk_fma_f32 v[100:101], v[142:143], v[112:113], v[100:101]
	v_cvt_pk_bf16_f32 v96, v112, v113
	v_cvt_pk_bf16_f32 v97, v114, v115
	v_cvt_pk_bf16_f32 v98, v116, v117
	v_cvt_pk_bf16_f32 v99, v118, v119
	s_nop 0
	v_cvt_pk_bf16_f32 v110, v104, v105
	v_cvt_pk_bf16_f32 v111, v106, v107
	v_mfma_f32_16x16x32_bf16 v[96:99], v[20:23], v[96:99], 0
	s_nop 0
	v_mfma_f32_16x16x32_bf16 v[96:99], v[24:27], v[108:111], v[96:99]
	v_mul_f32_e64 v108, v146, v102
	v_mul_f32_e64 v109, v147, v103
	v_pk_mul_f32 v[102:103], v[144:145], v[102:103]
	v_pk_fma_f32 v[110:111], v[144:145], v[114:115], v[108:109] neg_lo:[0,0,1] neg_hi:[0,0,1]
	v_pk_fma_f32 v[102:103], v[146:147], v[114:115], v[102:103]
	v_pk_fma_f32 v[108:109], v[140:141], v[112:113], v[120:121] neg_lo:[0,0,1] neg_hi:[0,0,1]
	v_pk_mul_f32 v[120:121], v[150:151], v[104:105]
	s_waitcnt vmcnt(11)
	v_mfma_f32_16x16x32_bf16 v[112:115], v[16:19], v[56:59], v[100:103]
	s_nop 2
	v_mul_f32_e64 v100, v154, v106
	v_mul_f32_e64 v101, v155, v107
	v_mfma_f32_16x16x32_bf16 v[108:111], v[12:15], v[56:59], v[108:111]
	v_fma_f32 v102, v152, v118, -v100
	v_fma_f32 v103, v153, v119, -v101
	v_pk_fma_f32 v[100:101], v[148:149], v[116:117], v[120:121] neg_lo:[0,0,1] neg_hi:[0,0,1]
	v_pk_mul_f32 v[106:107], v[152:153], v[106:107]
	v_pk_mul_f32 v[124:125], v[142:143], v[112:113]
	v_mfma_f32_16x16x32_bf16 v[120:123], v[4:7], v[56:59], v[100:103]
	s_nop 2
	v_mul_f32_e64 v100, v148, v104
	v_mul_f32_e64 v101, v149, v105
	v_pk_fma_f32 v[102:103], v[154:155], v[118:119], v[106:107]
	v_pk_fma_f32 v[100:101], v[150:151], v[116:117], v[100:101]
	v_cvt_pk_bf16_f32 v116, v112, v113
	v_cvt_pk_bf16_f32 v117, v114, v115
	v_mfma_f32_16x16x32_bf16 v[104:107], v[8:11], v[56:59], v[100:103]
	s_mov_b32 exec_hi, 0
	global_load_dwordx4 v[56:59], v[194:195], off
	s_mov_b32 exec_hi, -1
	v_lshl_add_u64 v[194:195], v[194:195], 0, v[206:207]
	s_cmp_lg_u32 s23, 0
	s_cbranch_scc1 .Ls5st_d2
	global_store_dwordx2 v[220:221], v[176:177], off
	s_branch .Ls5st_e2

; DI unsigned pack2(float a, float b) { f32x2_t v = {a, b}; bf16x2_t r = __builtin_convertvector(v, bf16x2_t); return __builtin_bit_cast(unsigned, r); }
; DI f32x4 mfma16(bf16x8 a, bf16x8 b, f32x4 c) { return __builtin_amdgcn_mfma_f32_16x16x32_bf16(a, b, c, 0, 0, 0); }
; DI void s5_job(const PX& p, int l, int job, unsigned char* smem) {
;     ...
;       if (active) {
;         if (blk + 1 < nblk) {
; #pragma unroll
;           for (int s = 0; s < 8; s++) {
;             const int st = (blk + 1) * 8 + s;
;             const int t = dir ? Lseg - 1 - st : st;
;             unext[s] = *(const uint4*)(Zu + (size_t)(tokbase + t) * 768);
;           }
;         }
; #pragma unroll
;         for (int s = 0; s < 8; s++) {
;           const bf16x8 ub = u4_to_bf8(ucur[s]);
; #pragma unroll
;           for (int tt = 0; tt < 2; tt++) {
;             f32x4 cr, ci;
; #pragma unroll
;             for (int r = 0; r < 4; r++) {
;               cr[r] = lre[tt][r] * sre[tt][r] - lim[tt][r] * sim[tt][r];
;               ci[r] = lre[tt][r] * sim[tt][r] + lim[tt][r] * sre[tt][r];
;             }
;             sre[tt] = mfma16(Are[tt], ub, cr);
;             sim[tt] = mfma16(Aim[tt], ub, ci);
;           }
;           uint4 pr, pi;
;           pr.x = pack2(sre[0][0], sre[0][1]); pr.y = pack2(sre[0][2], sre[0][3]);
;           pr.z = pack2(sre[1][0], sre[1][1]); pr.w = pack2(sre[1][2], sre[1][3]);
;           pi.x = pack2(sim[0][0], sim[0][1]); pi.y = pack2(sim[0][2], sim[0][3]);
;           pi.z = pack2(sim[1][0], sim[1][1]); pi.w = pack2(sim[1][2], sim[1][3]);
;           f32x4 y = f32x4{0.f, 0.f, 0.f, 0.f};
;           y = mfma16(Cf[0], u4_to_bf8(pr), y);
;           y = mfma16(Cf[1], u4_to_bf8(pi), y);
;           yp[s] = y;
;         }
.Ls5st_e2:
	v_mul_f32_e64 v112, v140, v112
	v_mul_f32_e64 v113, v141, v113
	s_nop 0
	v_cvt_pk_bf16_f32 v100, v108, v109
	v_cvt_pk_bf16_f32 v101, v110, v111
	v_cvt_pk_bf16_f32 v102, v120, v121
	v_cvt_pk_bf16_f32 v103, v122, v123
	s_nop 0
	v_cvt_pk_bf16_f32 v118, v104, v105
	v_cvt_pk_bf16_f32 v119, v106, v107
	v_mfma_f32_16x16x32_bf16 v[100:103], v[20:23], v[100:103], 0
	s_nop 0
	v_mfma_f32_16x16x32_bf16 v[100:103], v[24:27], v[116:119], v[100:103]
	v_mul_f32_e64 v116, v146, v114
	v_mul_f32_e64 v117, v147, v115
	v_pk_fma_f32 v[118:119], v[144:145], v[110:111], v[116:117] neg_lo:[0,0,1] neg_hi:[0,0,1]
	v_pk_fma_f32 v[116:117], v[140:141], v[108:109], v[124:125] neg_lo:[0,0,1] neg_hi:[0,0,1]
	v_pk_mul_f32 v[124:125], v[144:145], v[114:115]
	v_pk_fma_f32 v[108:109], v[142:143], v[108:109], v[112:113]
	s_waitcnt vmcnt(11)
	v_mfma_f32_16x16x32_bf16 v[114:117], v[12:15], v[52:55], v[116:119]
	v_mul_f32_e64 v112, v154, v106
	v_mul_f32_e64 v113, v155, v107
	v_pk_fma_f32 v[110:111], v[146:147], v[110:111], v[124:125]
	v_pk_fma_f32 v[126:127], v[152:153], v[122:123], v[112:113] neg_lo:[0,0,1] neg_hi:[0,0,1]
	v_pk_mul_f32 v[118:119], v[150:151], v[104:105]
	v_pk_mul_f32 v[106:107], v[152:153], v[106:107]
	v_pk_fma_f32 v[124:125], v[148:149], v[120:121], v[118:119] neg_lo:[0,0,1] neg_hi:[0,0,1]
	v_pk_mul_f32 v[104:105], v[148:149], v[104:105]
	v_pk_fma_f32 v[106:107], v[154:155], v[122:123], v[106:107]
	v_mfma_f32_16x16x32_bf16 v[124:127], v[4:7], v[52:55], v[124:127]
	v_fma_f32 v104, v150, v120, v104
	v_fma_f32 v105, v151, v121, v105
	v_mfma_f32_16x16x32_bf16 v[108:111], v[16:19], v[52:55], v[108:111]
	s_nop 0
	v_mfma_f32_16x16x32_bf16 v[118:121], v[8:11], v[52:55], v[104:107]
	s_mov_b32 exec_hi, 0
	global_load_dwordx4 v[52:55], v[196:197], off
	s_mov_b32 exec_hi, -1
	v_lshl_add_u64 v[196:197], v[196:197], 0, v[206:207]
	s_cmp_lg_u32 s23, 0
	s_cbranch_scc1 .Ls5st_d3
	global_store_dwordx2 v[222:223], v[180:181], off
	s_branch .Ls5st_e3

; DI unsigned pack2(float a, float b) { f32x2_t v = {a, b}; bf16x2_t r = __builtin_convertvector(v, bf16x2_t); return __builtin_bit_cast(unsigned, r); }
; DI f32x4 mfma16(bf16x8 a, bf16x8 b, f32x4 c) { return __builtin_amdgcn_mfma_f32_16x16x32_bf16(a, b, c, 0, 0, 0); }
; DI void s5_job(const PX& p, int l, int job, unsigned char* smem) {
;     ...
;       if (active) {
;         if (blk + 1 < nblk) {
; #pragma unroll
;           for (int s = 0; s < 8; s++) {
;             const int st = (blk + 1) * 8 + s;
;             const int t = dir ? Lseg - 1 - st : st;
;             unext[s] = *(const uint4*)(Zu + (size_t)(tokbase + t) * 768);
;           }
;         }
; #pragma unroll
;         for (int s = 0; s < 8; s++) {
;           const bf16x8 ub = u4_to_bf8(ucur[s]);
; #pragma unroll
;           for (int tt = 0; tt < 2; tt++) {
;             f32x4 cr, ci;
; #pragma unroll
;             for (int r = 0; r < 4; r++) {
;               cr[r] = lre[tt][r] * sre[tt][r] - lim[tt][r] * sim[tt][r];
;               ci[r] = lre[tt][r] * sim[tt][r] + lim[tt][r] * sre[tt][r];
;             }
;             sre[tt] = mfma16(Are[tt], ub, cr);
;             sim[tt] = mfma16(Aim[tt], ub, ci);
;           }
;           uint4 pr, pi;
;           pr.x = pack2(sre[0][0], sre[0][1]); pr.y = pack2(sre[0][2], sre[0][3]);
;           pr.z = pack2(sre[1][0], sre[1][1]); pr.w = pack2(sre[1][2], sre[1][3]);
;           pi.x = pack2(sim[0][0], sim[0][1]); pi.y = pack2(sim[0][2], sim[0][3]);
;           pi.z = pack2(sim[1][0], sim[1][1]); pi.w = pack2(sim[1][2], sim[1][3]);
;           f32x4 y = f32x4{0.f, 0.f, 0.f, 0.f};
;           y = mfma16(Cf[0], u4_to_bf8(pr), y);
;           y = mfma16(Cf[1], u4_to_bf8(pi), y);
;           yp[s] = y;
;         }
.Ls5st_e3:
	s_nop 2
	v_cvt_pk_bf16_f32 v104, v114, v115
	v_cvt_pk_bf16_f32 v105, v116, v117
	v_cvt_pk_bf16_f32 v106, v124, v125
	v_cvt_pk_bf16_f32 v107, v126, v127
	v_cvt_pk_bf16_f32 v128, v108, v109
	v_cvt_pk_bf16_f32 v129, v110, v111
	v_mfma_f32_16x16x32_bf16 v[104:107], v[20:23], v[104:107], 0
	v_cvt_pk_bf16_f32 v130, v118, v119
	v_cvt_pk_bf16_f32 v131, v120, v121
	v_pk_mul_f32 v[122:123], v[142:143], v[108:109]
	v_pk_mul_f32 v[112:113], v[146:147], v[110:111]
	v_mfma_f32_16x16x32_bf16 v[104:107], v[24:27], v[128:131], v[104:107]
	v_fma_f32 v128, v140, v114, -v122
	v_fma_f32 v129, v141, v115, -v123
	v_pk_mul_f32 v[122:123], v[144:145], v[110:111]
	v_pk_mul_f32 v[108:109], v[140:141], v[108:109]
	v_pk_fma_f32 v[130:131], v[144:145], v[116:117], v[112:113] neg_lo:[0,0,1] neg_hi:[0,0,1]
	v_pk_fma_f32 v[116:117], v[146:147], v[116:117], v[122:123]
	v_pk_fma_f32 v[114:115], v[142:143], v[114:115], v[108:109]
	v_pk_mul_f32 v[108:109], v[154:155], v[120:121]
	v_pk_mul_f32 v[122:123], v[150:151], v[118:119]
	s_waitcnt vmcnt(11)
	v_mfma_f32_16x16x32_bf16 v[110:113], v[12:15], v[72:75], v[128:131]
	v_mul_f32_e64 v118, v148, v118
	v_mul_f32_e64 v119, v149, v119
	s_nop 0
	v_pk_fma_f32 v[130:131], v[152:153], v[126:127], v[108:109] neg_lo:[0,0,1] neg_hi:[0,0,1]
	v_pk_fma_f32 v[128:129], v[148:149], v[124:125], v[122:123] neg_lo:[0,0,1] neg_hi:[0,0,1]
	v_pk_mul_f32 v[108:109], v[152:153], v[120:121]
	v_pk_fma_f32 v[124:125], v[150:151], v[124:125], v[118:119]
	v_mfma_f32_16x16x32_bf16 v[120:123], v[4:7], v[72:75], v[128:131]
	v_fma_f32 v126, v154, v126, v108
	v_fma_f32 v127, v155, v127, v109
	v_mfma_f32_16x16x32_bf16 v[114:117], v[16:19], v[72:75], v[114:117]
	s_nop 0
	v_mfma_f32_16x16x32_bf16 v[128:131], v[8:11], v[72:75], v[124:127]
	s_mov_b32 exec_hi, 0
	global_load_dwordx4 v[72:75], v[198:199], off
	s_mov_b32 exec_hi, -1
	v_lshl_add_u64 v[198:199], v[198:199], 0, v[206:207]
	s_nop 2
	v_cvt_pk_bf16_f32 v124, v110, v111
	v_cvt_pk_bf16_f32 v125, v112, v113
	v_cvt_pk_bf16_f32 v126, v120, v121
	v_cvt_pk_bf16_f32 v127, v122, v123
	v_cvt_pk_bf16_f32 v132, v114, v115
	v_cvt_pk_bf16_f32 v133, v116, v117
	v_mfma_f32_16x16x32_bf16 v[124:127], v[20:23], v[124:127], 0
	v_cvt_pk_bf16_f32 v134, v128, v129
	v_cvt_pk_bf16_f32 v135, v130, v131
	v_pk_mul_f32 v[108:109], v[146:147], v[116:117]
	v_pk_mul_f32 v[118:119], v[142:143], v[114:115]
	v_mfma_f32_16x16x32_bf16 v[124:127], v[24:27], v[132:135], v[124:127]
	v_fma_f32 v134, v144, v112, -v108
	v_fma_f32 v135, v145, v113, -v109
	v_pk_mul_f32 v[108:109], v[144:145], v[116:117]
	v_pk_mul_f32 v[114:115], v[140:141], v[114:115]
	v_pk_fma_f32 v[132:133], v[140:141], v[110:111], v[118:119] neg_lo:[0,0,1] neg_hi:[0,0,1]
	v_pk_fma_f32 v[112:113], v[146:147], v[112:113], v[108:109]
	v_pk_fma_f32 v[110:111], v[142:143], v[110:111], v[114:115]
	s_waitcnt vmcnt(11)
	v_mfma_f32_16x16x32_bf16 v[116:119], v[12:15], v[68:71], v[132:135]
	v_mfma_f32_16x16x32_bf16 v[108:111], v[16:19], v[68:71], v[110:113]
	s_nop 1
	v_mul_f32_e64 v132, v150, v128
	v_mul_f32_e64 v133, v151, v129
	v_pk_mul_f32 v[128:129], v[148:149], v[128:129]
	v_pk_mul_f32 v[112:113], v[154:155], v[130:131]
	v_pk_mul_f32 v[130:131], v[152:153], v[130:131]
	v_pk_fma_f32 v[114:115], v[152:153], v[122:123], v[112:113] neg_lo:[0,0,1] neg_hi:[0,0,1]
	v_pk_fma_f32 v[112:113], v[148:149], v[120:121], v[132:133] neg_lo:[0,0,1] neg_hi:[0,0,1]
	v_pk_fma_f32 v[122:123], v[154:155], v[122:123], v[130:131]
	v_pk_fma_f32 v[120:121], v[150:151], v[120:121], v[128:129]
	v_mfma_f32_16x16x32_bf16 v[112:115], v[4:7], v[68:71], v[112:115]
	v_cvt_pk_bf16_f32 v128, v116, v117
	v_cvt_pk_bf16_f32 v129, v118, v119
	v_cvt_pk_bf16_f32 v132, v108, v109
	v_mfma_f32_16x16x32_bf16 v[120:123], v[8:11], v[68:71], v[120:123]
	s_mov_b32 exec_hi, 0
	global_load_dwordx4 v[68:71], v[200:201], off
	s_mov_b32 exec_hi, -1
	v_lshl_add_u64 v[200:201], v[200:201], 0, v[206:207]
	v_cvt_pk_bf16_f32 v133, v110, v111
	s_nop 2
	v_cvt_pk_bf16_f32 v130, v112, v113
	v_cvt_pk_bf16_f32 v131, v114, v115
	v_pk_mul_f32 v[136:137], v[142:143], v[108:109]
	v_pk_mul_f32 v[108:109], v[140:141], v[108:109]
	v_mfma_f32_16x16x32_bf16 v[128:131], v[20:23], v[128:131], 0
	v_cvt_pk_bf16_f32 v134, v120, v121
	v_cvt_pk_bf16_f32 v135, v122, v123
	v_pk_fma_f32 v[108:109], v[142:143], v[116:117], v[108:109]
	s_nop 0
	v_mfma_f32_16x16x32_bf16 v[128:131], v[24:27], v[132:135], v[128:131]
	v_mul_f32_e64 v132, v146, v110
	v_mul_f32_e64 v133, v147, v111
	v_pk_mul_f32 v[110:111], v[144:145], v[110:111]
	v_pk_fma_f32 v[134:135], v[144:145], v[118:119], v[132:133] neg_lo:[0,0,1] neg_hi:[0,0,1]
	v_pk_fma_f32 v[132:133], v[140:141], v[116:117], v[136:137] neg_lo:[0,0,1] neg_hi:[0,0,1]
	v_pk_mul_f32 v[116:117], v[154:155], v[122:123]
	v_pk_fma_f32 v[110:111], v[146:147], v[118:119], v[110:111]
	s_waitcnt vmcnt(11)
; DI unsigned pack2(float a, float b) { f32x2_t v = {a, b}; bf16x2_t r = __builtin_convertvector(v, bf16x2_t); return __builtin_bit_cast(unsigned, r); }
; DI f32x4 mfma16(bf16x8 a, bf16x8 b, f32x4 c) { return __builtin_amdgcn_mfma_f32_16x16x32_bf16(a, b, c, 0, 0, 0); }
; DI void s5_job(const PX& p, int l, int job, unsigned char* smem) {
;     ...
;         for (int s = 0; s < 8; s++) {
;           const bf16x8 ub = u4_to_bf8(ucur[s]);
; #pragma unroll
;           for (int tt = 0; tt < 2; tt++) {
;             f32x4 cr, ci;
; #pragma unroll
;             for (int r = 0; r < 4; r++) {
;               cr[r] = lre[tt][r] * sre[tt][r] - lim[tt][r] * sim[tt][r];
;               ci[r] = lre[tt][r] * sim[tt][r] + lim[tt][r] * sre[tt][r];
;             }
;             sre[tt] = mfma16(Are[tt], ub, cr);
;             sim[tt] = mfma16(Aim[tt], ub, ci);
;           }
;           uint4 pr, pi;
;           pr.x = pack2(sre[0][0], sre[0][1]); pr.y = pack2(sre[0][2], sre[0][3]);
;           pr.z = pack2(sre[1][0], sre[1][1]); pr.w = pack2(sre[1][2], sre[1][3]);
;           pi.x = pack2(sim[0][0], sim[0][1]); pi.y = pack2(sim[0][2], sim[0][3]);
;           pi.z = pack2(sim[1][0], sim[1][1]); pi.w = pack2(sim[1][2], sim[1][3]);
;           f32x4 y = f32x4{0.f, 0.f, 0.f, 0.f};
;           y = mfma16(Cf[0], u4_to_bf8(pr), y);
;           y = mfma16(Cf[1], u4_to_bf8(pi), y);
;           yp[s] = y;
;         }
;         if (hf == 1) {
; #pragma unroll
;           for (int s = 0; s < 8; s++)
; #pragma unroll
;             for (int r = 0; r < 4; r++) exb[(s * 4 + r) * 64] = yp[s][r];
;         }
	v_mfma_f32_16x16x32_bf16 v[136:139], v[12:15], v[88:91], v[132:135]
	v_fma_f32 v118, v152, v114, -v116
	v_fma_f32 v119, v153, v115, -v117
	v_pk_mul_f32 v[122:123], v[152:153], v[122:123]
	v_pk_mul_f32 v[132:133], v[150:151], v[120:121]
	v_pk_fma_f32 v[114:115], v[154:155], v[114:115], v[122:123]
	v_pk_fma_f32 v[116:117], v[148:149], v[112:113], v[132:133] neg_lo:[0,0,1] neg_hi:[0,0,1]
	v_mfma_f32_16x16x32_bf16 v[108:111], v[16:19], v[88:91], v[108:111]
	s_nop 0
	v_mfma_f32_16x16x32_bf16 v[164:167], v[4:7], v[88:91], v[116:119]
	s_nop 2
	v_mul_f32_e64 v116, v148, v120
	v_mul_f32_e64 v117, v149, v121
	s_nop 0
	v_cvt_pk_bf16_f32 v120, v108, v109
	v_pk_fma_f32 v[112:113], v[150:151], v[112:113], v[116:117]
	v_cvt_pk_bf16_f32 v116, v136, v137
	v_cvt_pk_bf16_f32 v117, v138, v139
	v_mfma_f32_16x16x32_bf16 v[112:115], v[8:11], v[88:91], v[112:115]
	s_mov_b32 exec_hi, 0
	global_load_dwordx4 v[88:91], v[202:203], off
	s_mov_b32 exec_hi, -1
	v_lshl_add_u64 v[202:203], v[202:203], 0, v[206:207]
	v_cvt_pk_bf16_f32 v118, v164, v165
	v_cvt_pk_bf16_f32 v119, v166, v167
	v_cvt_pk_bf16_f32 v121, v110, v111
	s_nop 0
	v_mfma_f32_16x16x32_bf16 v[116:119], v[20:23], v[116:119], 0
	s_nop 2
	v_cvt_pk_bf16_f32 v122, v112, v113
	v_cvt_pk_bf16_f32 v123, v114, v115
	s_nop 1
	v_mfma_f32_16x16x32_bf16 v[132:135], v[24:27], v[120:123], v[116:119]
	v_mul_f32_e64 v120, v142, v108
	v_mul_f32_e64 v121, v143, v109
	v_pk_mul_f32 v[108:109], v[140:141], v[108:109]
	v_pk_mul_f32 v[116:117], v[146:147], v[110:111]
	v_pk_mul_f32 v[110:111], v[144:145], v[110:111]
	v_pk_fma_f32 v[108:109], v[142:143], v[136:137], v[108:109]
	v_pk_fma_f32 v[110:111], v[146:147], v[138:139], v[110:111]
	v_pk_fma_f32 v[118:119], v[144:145], v[138:139], v[116:117] neg_lo:[0,0,1] neg_hi:[0,0,1]
	v_pk_fma_f32 v[116:117], v[140:141], v[136:137], v[120:121] neg_lo:[0,0,1] neg_hi:[0,0,1]
	s_waitcnt vmcnt(11)
	v_mfma_f32_16x16x32_bf16 v[120:123], v[16:19], v[84:87], v[108:111]
	v_mul_f32_e64 v136, v150, v112
	v_mul_f32_e64 v137, v151, v113
	v_pk_mul_f32 v[112:113], v[148:149], v[112:113]
	v_pk_mul_f32 v[108:109], v[154:155], v[114:115]
	v_mfma_f32_16x16x32_bf16 v[116:119], v[12:15], v[84:87], v[116:119]
	v_fma_f32 v110, v152, v166, -v108
	v_fma_f32 v111, v153, v167, -v109
	v_pk_fma_f32 v[108:109], v[148:149], v[164:165], v[136:137] neg_lo:[0,0,1] neg_hi:[0,0,1]
	v_pk_mul_f32 v[114:115], v[152:153], v[114:115]
	v_pk_fma_f32 v[112:113], v[150:151], v[164:165], v[112:113]
	v_mfma_f32_16x16x32_bf16 v[108:111], v[4:7], v[84:87], v[108:111]
	v_fma_f32 v114, v154, v166, v114
	v_fma_f32 v115, v155, v167, v115
	v_cvt_pk_bf16_f32 v136, v116, v117
	v_cvt_pk_bf16_f32 v137, v118, v119
	v_mfma_f32_16x16x32_bf16 v[112:115], v[8:11], v[84:87], v[112:115]
	s_mov_b32 exec_hi, 0
	global_load_dwordx4 v[84:87], v[204:205], off
	s_mov_b32 exec_hi, -1
	v_lshl_add_u64 v[204:205], v[204:205], 0, v[206:207]
	v_cvt_pk_bf16_f32 v164, v120, v121
	s_nop 1
	v_cvt_pk_bf16_f32 v138, v108, v109
	v_cvt_pk_bf16_f32 v139, v110, v111
	v_cvt_pk_bf16_f32 v165, v122, v123
	s_nop 0
	v_mfma_f32_16x16x32_bf16 v[136:139], v[20:23], v[136:139], 0
	v_cvt_pk_bf16_f32 v166, v112, v113
	v_cvt_pk_bf16_f32 v167, v114, v115
	s_nop 1
	v_mfma_f32_16x16x32_bf16 v[136:139], v[24:27], v[164:167], v[136:139]
	v_mad_u32_u24 v163, v211, 12, v0
	s_and_saveexec_b64 s[16:17], s[8:9]
	s_cbranch_execz .Ls5x_w0
	ds_write_b128 v163, v[92:95]
	ds_write_b128 v163, v[96:99] offset:1024
	ds_write_b128 v163, v[100:103] offset:2048
	ds_write_b128 v163, v[104:107] offset:3072
